# decode-step retention state outputs stored write-through (sc1): no dirty L2 lines left for the next barrier's write-back; on top of conv write-through
# speedup vs baseline: 1.0082x; 1.0082x over previous
; #define LAS __attribute__((address_space(3)))
; template <bool STORE> __device__ __forceinline__ void ret_sample_item(LAS unsigned char* lds, int db, int h, bf16* Qb, const bf16* Kb, const bf16* Vb, const bf16* Gb, const f32x2* tab, const float* s_in, float* s_out) {
;     ...
;         f32x4 vv[8], cr[8];
; #pragma unroll
;         for (int j = 0; j < 8; ++j) { vv[j] = *(const LAS f32x4*)(vS + j * 128 + e4); cr[j] = (f32x4){0.f, 0.f, 0.f, 0.f}; }
;         const float g8 = __expf(lg * (float)DSEQ);
;         float* op = s_out + (size_t)(dg * 8) * HD + e4;
; #pragma unroll
;         for (int dl = 0; dl < 8; ++dl) {
;             const int d = dg * 8 + dl; const f32x4 s = st[dl];
;             const f32x4 qa = *(const LAS f32x4*)(qT + d * 8), qb = *(const LAS f32x4*)(qT + d * 8 + 4);
;             const f32x4 ka = *(const LAS f32x4*)(kT + d * 8), kb = *(const LAS f32x4*)(kT + d * 8 + 4);
;             cr[0] += s * qa.x; cr[1] += s * qa.y; cr[2] += s * qa.z; cr[3] += s * qa.w; cr[4] += s * qb.x; cr[5] += s * qb.y; cr[6] += s * qb.z; cr[7] += s * qb.w;
;             f32x4 sn = s * g8;
;             sn += vv[0] * ka.x; sn += vv[1] * ka.y; sn += vv[2] * ka.z; sn += vv[3] * ka.w; sn += vv[4] * kb.x; sn += vv[5] * kb.y; sn += vv[6] * kb.z; sn += vv[7] * kb.w;
;             if (STORE) *(f32x4*)(op + (size_t)dl * HD) = sn;
.LBB0_510:
	s_or_b64 exec, exec, s[14:15]
	v_mov_b32_e32 v76, 0x41000000
	v_lshlrev_b64 v[74:75], 7, v[72:73]
	v_add_u32_e32 v73, 0, v188
	v_mul_f32_e32 v76, s20, v76
	v_lshl_add_u32 v85, v72, 5, 0
	ds_read_b128 v[44:47], v73 offset:8192
	ds_read_b128 v[40:43], v73 offset:8704
	ds_read_b128 v[36:39], v73 offset:9216
	ds_read_b128 v[32:35], v73 offset:9728
	ds_read_b128 v[28:31], v73 offset:10240
	ds_read_b128 v[24:27], v73 offset:10752
	ds_read_b128 v[20:23], v73 offset:11264
	s_waitcnt lgkmcnt(7)
	ds_read_b128 v[16:19], v73 offset:11776
	v_mul_f32_e32 v76, 0x3fb8aa3b, v76
	ds_read_b128 v[86:89], v85
	ds_read_b128 v[90:93], v85 offset:4096
	ds_read_b128 v[94:97], v85 offset:4112
	ds_read_b128 v[98:101], v85 offset:16
	ds_read_b128 v[102:105], v85 offset:32
	ds_read_b128 v[106:109], v85 offset:48
	v_exp_f32_e32 v76, v76
	s_waitcnt vmcnt(7) lgkmcnt(5)
	v_pk_fma_f32 v[110:111], v[60:61], v[86:87], 0 op_sel_hi:[1,0,0]
	v_pk_fma_f32 v[112:113], v[62:63], v[86:87], 0 op_sel_hi:[1,0,0]
	v_pk_fma_f32 v[114:115], v[60:61], v[86:87], 0 op_sel:[0,1,0] op_sel_hi:[1,1,0]
	v_pk_fma_f32 v[116:117], v[62:63], v[86:87], 0 op_sel:[0,1,0] op_sel_hi:[1,1,0]
	v_mov_b32_e32 v86, v89
	v_pk_fma_f32 v[122:123], v[60:61], v[86:87], 0 op_sel_hi:[1,0,0]
	v_pk_fma_f32 v[124:125], v[62:63], v[86:87], 0 op_sel_hi:[1,0,0]
	s_waitcnt lgkmcnt(2)
	v_mov_b32_e32 v86, v101
	v_pk_fma_f32 v[118:119], v[60:61], v[88:89], 0 op_sel_hi:[1,0,0]
	v_pk_fma_f32 v[120:121], v[62:63], v[88:89], 0 op_sel_hi:[1,0,0]
	v_pk_fma_f32 v[132:133], v[60:61], v[100:101], 0 op_sel_hi:[1,0,0]
	v_pk_fma_f32 v[134:135], v[62:63], v[100:101], 0 op_sel_hi:[1,0,0]
	v_pk_fma_f32 v[100:101], v[60:61], v[86:87], 0 op_sel_hi:[1,0,0]
	v_pk_fma_f32 v[136:137], v[62:63], v[86:87], 0 op_sel_hi:[1,0,0]
	v_pk_mul_f32 v[86:87], v[46:47], v[90:91] op_sel_hi:[1,0]
	v_pk_mul_f32 v[88:89], v[44:45], v[90:91] op_sel_hi:[1,0]
	v_pk_fma_f32 v[126:127], v[60:61], v[98:99], 0 op_sel_hi:[1,0,0]
	v_pk_fma_f32 v[128:129], v[62:63], v[98:99], 0 op_sel_hi:[1,0,0]
	v_pk_fma_f32 v[130:131], v[60:61], v[98:99], 0 op_sel:[0,1,0] op_sel_hi:[1,1,0]
	v_pk_fma_f32 v[98:99], v[62:63], v[98:99], 0 op_sel:[0,1,0] op_sel_hi:[1,1,0]
	v_pk_fma_f32 v[62:63], v[62:63], v[76:77], v[86:87] op_sel_hi:[1,0,1]
	v_pk_fma_f32 v[60:61], v[60:61], v[76:77], v[88:89] op_sel_hi:[1,0,1]
	v_pk_fma_f32 v[62:63], v[42:43], v[90:91], v[62:63] op_sel:[0,1,0]
	v_pk_fma_f32 v[60:61], v[40:41], v[90:91], v[60:61] op_sel:[0,1,0]
	v_pk_fma_f32 v[62:63], v[38:39], v[92:93], v[62:63] op_sel_hi:[1,0,1]
	v_pk_fma_f32 v[60:61], v[36:37], v[92:93], v[60:61] op_sel_hi:[1,0,1]
	v_mov_b32_e32 v86, v93
	v_pk_fma_f32 v[60:61], v[32:33], v[86:87], v[60:61] op_sel_hi:[1,0,1]
	v_pk_fma_f32 v[62:63], v[34:35], v[86:87], v[62:63] op_sel_hi:[1,0,1]
	s_add_u32 s8, s17, s8
	v_pk_fma_f32 v[62:63], v[30:31], v[94:95], v[62:63] op_sel_hi:[1,0,1]
	v_pk_fma_f32 v[60:61], v[28:29], v[94:95], v[60:61] op_sel_hi:[1,0,1]
	s_addc_u32 s9, s18, s9
	v_pk_fma_f32 v[60:61], v[24:25], v[94:95], v[60:61] op_sel:[0,1,0]
	v_pk_fma_f32 v[62:63], v[26:27], v[94:95], v[62:63] op_sel:[0,1,0]
	v_lshl_add_u64 v[74:75], v[74:75], 2, s[8:9]
	v_pk_fma_f32 v[62:63], v[22:23], v[96:97], v[62:63] op_sel_hi:[1,0,1]
	v_pk_fma_f32 v[60:61], v[20:21], v[96:97], v[60:61] op_sel_hi:[1,0,1]
	v_mov_b32_e32 v86, v97
	v_lshl_add_u64 v[74:75], v[74:75], 0, v[188:189]
	v_pk_fma_f32 v[60:61], v[16:17], v[86:87], v[60:61] op_sel_hi:[1,0,1]
	v_pk_fma_f32 v[62:63], v[18:19], v[86:87], v[62:63] op_sel_hi:[1,0,1]
	global_store_dwordx4 v[74:75], v[60:63], off sc1
	ds_read_b128 v[60:63], v85 offset:4128
	ds_read_b128 v[86:89], v85 offset:4144
	s_waitcnt lgkmcnt(3)
	v_mov_b32_e32 v90, v105
	s_waitcnt vmcnt(7)
	v_pk_fma_f32 v[112:113], v[58:59], v[102:103], v[112:113] op_sel_hi:[1,0,1]
	v_pk_fma_f32 v[110:111], v[56:57], v[102:103], v[110:111] op_sel_hi:[1,0,1]
	v_pk_fma_f32 v[116:117], v[58:59], v[102:103], v[116:117] op_sel:[0,1,0]
	v_pk_fma_f32 v[102:103], v[56:57], v[102:103], v[114:115] op_sel:[0,1,0]
	v_pk_fma_f32 v[114:115], v[58:59], v[104:105], v[120:121] op_sel_hi:[1,0,1]
	v_pk_fma_f32 v[118:119], v[56:57], v[104:105], v[118:119] op_sel_hi:[1,0,1]
	v_pk_fma_f32 v[104:105], v[58:59], v[90:91], v[124:125] op_sel_hi:[1,0,1]
	v_pk_fma_f32 v[120:121], v[56:57], v[90:91], v[122:123] op_sel_hi:[1,0,1]
	s_waitcnt lgkmcnt(2)
	v_mov_b32_e32 v90, v109
	v_pk_fma_f32 v[122:123], v[58:59], v[106:107], v[128:129] op_sel_hi:[1,0,1]
	v_pk_fma_f32 v[124:125], v[56:57], v[106:107], v[126:127] op_sel_hi:[1,0,1]
	v_pk_fma_f32 v[126:127], v[58:59], v[106:107], v[98:99] op_sel:[0,1,0]
	v_pk_fma_f32 v[106:107], v[56:57], v[106:107], v[130:131] op_sel:[0,1,0]
	v_pk_fma_f32 v[128:129], v[58:59], v[108:109], v[134:135] op_sel_hi:[1,0,1]
	v_pk_fma_f32 v[130:131], v[56:57], v[108:109], v[132:133] op_sel_hi:[1,0,1]
	v_pk_fma_f32 v[108:109], v[58:59], v[90:91], v[136:137] op_sel_hi:[1,0,1]
	v_pk_fma_f32 v[132:133], v[56:57], v[90:91], v[100:101] op_sel_hi:[1,0,1]
	s_waitcnt lgkmcnt(1)
	v_pk_mul_f32 v[90:91], v[46:47], v[60:61] op_sel_hi:[1,0]
	v_pk_mul_f32 v[92:93], v[44:45], v[60:61] op_sel_hi:[1,0]
	v_pk_fma_f32 v[58:59], v[58:59], v[76:77], v[90:91] op_sel_hi:[1,0,1]
	v_pk_fma_f32 v[56:57], v[56:57], v[76:77], v[92:93] op_sel_hi:[1,0,1]
	v_pk_fma_f32 v[58:59], v[42:43], v[60:61], v[58:59] op_sel:[0,1,0]
	v_pk_fma_f32 v[56:57], v[40:41], v[60:61], v[56:57] op_sel:[0,1,0]
	v_pk_fma_f32 v[58:59], v[38:39], v[62:63], v[58:59] op_sel_hi:[1,0,1]
	v_pk_fma_f32 v[56:57], v[36:37], v[62:63], v[56:57] op_sel_hi:[1,0,1]
	v_mov_b32_e32 v60, v63
	v_pk_fma_f32 v[56:57], v[32:33], v[60:61], v[56:57] op_sel_hi:[1,0,1]
	v_pk_fma_f32 v[58:59], v[34:35], v[60:61], v[58:59] op_sel_hi:[1,0,1]
	s_waitcnt lgkmcnt(0)
; #define LAS __attribute__((address_space(3)))
; template <bool STORE> __device__ __forceinline__ void ret_sample_item(LAS unsigned char* lds, int db, int h, bf16* Qb, const bf16* Kb, const bf16* Vb, const bf16* Gb, const f32x2* tab, const float* s_in, float* s_out) {
;     ...
;         for (int dl = 0; dl < 8; ++dl) {
;             const int d = dg * 8 + dl; const f32x4 s = st[dl];
;             const f32x4 qa = *(const LAS f32x4*)(qT + d * 8), qb = *(const LAS f32x4*)(qT + d * 8 + 4);
;             const f32x4 ka = *(const LAS f32x4*)(kT + d * 8), kb = *(const LAS f32x4*)(kT + d * 8 + 4);
;             cr[0] += s * qa.x; cr[1] += s * qa.y; cr[2] += s * qa.z; cr[3] += s * qa.w; cr[4] += s * qb.x; cr[5] += s * qb.y; cr[6] += s * qb.z; cr[7] += s * qb.w;
;             f32x4 sn = s * g8;
;             sn += vv[0] * ka.x; sn += vv[1] * ka.y; sn += vv[2] * ka.z; sn += vv[3] * ka.w; sn += vv[4] * kb.x; sn += vv[5] * kb.y; sn += vv[6] * kb.z; sn += vv[7] * kb.w;
;             if (STORE) *(f32x4*)(op + (size_t)dl * HD) = sn;
	v_pk_fma_f32 v[56:57], v[28:29], v[86:87], v[56:57] op_sel_hi:[1,0,1]
	v_pk_fma_f32 v[58:59], v[30:31], v[86:87], v[58:59] op_sel_hi:[1,0,1]
	v_pk_fma_f32 v[56:57], v[24:25], v[86:87], v[56:57] op_sel:[0,1,0]
	v_pk_fma_f32 v[58:59], v[26:27], v[86:87], v[58:59] op_sel:[0,1,0]
	v_pk_fma_f32 v[56:57], v[20:21], v[88:89], v[56:57] op_sel_hi:[1,0,1]
	v_pk_fma_f32 v[58:59], v[22:23], v[88:89], v[58:59] op_sel_hi:[1,0,1]
	v_mov_b32_e32 v60, v89
	v_pk_fma_f32 v[56:57], v[16:17], v[60:61], v[56:57] op_sel_hi:[1,0,1]
	v_pk_fma_f32 v[58:59], v[18:19], v[60:61], v[58:59] op_sel_hi:[1,0,1]
	global_store_dwordx4 v[74:75], v[56:59], off offset:512 sc1
	ds_read_b128 v[56:59], v85 offset:64
	ds_read_b128 v[60:63], v85 offset:4160
	ds_read_b128 v[86:89], v85 offset:4176
	ds_read_b128 v[90:93], v85 offset:80
	ds_read_b128 v[94:97], v85 offset:96
	ds_read_b128 v[98:101], v85 offset:112
	s_waitcnt vmcnt(7) lgkmcnt(5)
	v_pk_fma_f32 v[110:111], v[52:53], v[56:57], v[110:111] op_sel_hi:[1,0,1]
	v_pk_fma_f32 v[112:113], v[54:55], v[56:57], v[112:113] op_sel_hi:[1,0,1]
	v_pk_fma_f32 v[102:103], v[52:53], v[56:57], v[102:103] op_sel:[0,1,0]
	v_pk_fma_f32 v[116:117], v[54:55], v[56:57], v[116:117] op_sel:[0,1,0]
	v_mov_b32_e32 v56, v59
	v_pk_fma_f32 v[120:121], v[52:53], v[56:57], v[120:121] op_sel_hi:[1,0,1]
	v_pk_fma_f32 v[104:105], v[54:55], v[56:57], v[104:105] op_sel_hi:[1,0,1]
	s_waitcnt lgkmcnt(2)
	v_mov_b32_e32 v56, v93
	v_pk_fma_f32 v[118:119], v[52:53], v[58:59], v[118:119] op_sel_hi:[1,0,1]
	v_pk_fma_f32 v[114:115], v[54:55], v[58:59], v[114:115] op_sel_hi:[1,0,1]
	v_pk_fma_f32 v[124:125], v[52:53], v[90:91], v[124:125] op_sel_hi:[1,0,1]
	v_pk_fma_f32 v[122:123], v[54:55], v[90:91], v[122:123] op_sel_hi:[1,0,1]
	v_pk_fma_f32 v[106:107], v[52:53], v[90:91], v[106:107] op_sel:[0,1,0]
	v_pk_fma_f32 v[90:91], v[54:55], v[90:91], v[126:127] op_sel:[0,1,0]
	v_pk_fma_f32 v[126:127], v[52:53], v[92:93], v[130:131] op_sel_hi:[1,0,1]
	v_pk_fma_f32 v[128:129], v[54:55], v[92:93], v[128:129] op_sel_hi:[1,0,1]
	v_pk_fma_f32 v[92:93], v[52:53], v[56:57], v[132:133] op_sel_hi:[1,0,1]
	v_pk_fma_f32 v[108:109], v[54:55], v[56:57], v[108:109] op_sel_hi:[1,0,1]
	v_pk_mul_f32 v[56:57], v[46:47], v[60:61] op_sel_hi:[1,0]
	v_pk_mul_f32 v[58:59], v[44:45], v[60:61] op_sel_hi:[1,0]
	v_pk_fma_f32 v[54:55], v[54:55], v[76:77], v[56:57] op_sel_hi:[1,0,1]
	v_pk_fma_f32 v[52:53], v[52:53], v[76:77], v[58:59] op_sel_hi:[1,0,1]
	v_pk_fma_f32 v[54:55], v[42:43], v[60:61], v[54:55] op_sel:[0,1,0]
	v_pk_fma_f32 v[52:53], v[40:41], v[60:61], v[52:53] op_sel:[0,1,0]
	v_pk_fma_f32 v[54:55], v[38:39], v[62:63], v[54:55] op_sel_hi:[1,0,1]
	v_pk_fma_f32 v[52:53], v[36:37], v[62:63], v[52:53] op_sel_hi:[1,0,1]
	v_mov_b32_e32 v56, v63
	v_pk_fma_f32 v[54:55], v[34:35], v[56:57], v[54:55] op_sel_hi:[1,0,1]
	v_pk_fma_f32 v[52:53], v[32:33], v[56:57], v[52:53] op_sel_hi:[1,0,1]
	v_pk_fma_f32 v[54:55], v[30:31], v[86:87], v[54:55] op_sel_hi:[1,0,1]
	v_pk_fma_f32 v[52:53], v[28:29], v[86:87], v[52:53] op_sel_hi:[1,0,1]
	v_pk_fma_f32 v[54:55], v[26:27], v[86:87], v[54:55] op_sel:[0,1,0]
	v_pk_fma_f32 v[52:53], v[24:25], v[86:87], v[52:53] op_sel:[0,1,0]
	v_pk_fma_f32 v[54:55], v[22:23], v[88:89], v[54:55] op_sel_hi:[1,0,1]
	v_pk_fma_f32 v[52:53], v[20:21], v[88:89], v[52:53] op_sel_hi:[1,0,1]
	v_mov_b32_e32 v56, v89
	v_pk_fma_f32 v[54:55], v[18:19], v[56:57], v[54:55] op_sel_hi:[1,0,1]
	v_pk_fma_f32 v[52:53], v[16:17], v[56:57], v[52:53] op_sel_hi:[1,0,1]
	global_store_dwordx4 v[74:75], v[52:55], off offset:1024 sc1
	ds_read_b128 v[52:55], v85 offset:4192
	ds_read_b128 v[56:59], v85 offset:4208
	s_waitcnt lgkmcnt(3)
	v_mov_b32_e32 v60, v97
	s_waitcnt vmcnt(7)
	v_pk_fma_f32 v[86:87], v[50:51], v[94:95], v[112:113] op_sel_hi:[1,0,1]
	v_pk_fma_f32 v[88:89], v[48:49], v[94:95], v[110:111] op_sel_hi:[1,0,1]
	v_pk_fma_f32 v[110:111], v[50:51], v[94:95], v[116:117] op_sel:[0,1,0]
	v_pk_fma_f32 v[94:95], v[48:49], v[94:95], v[102:103] op_sel:[0,1,0]
	v_pk_fma_f32 v[102:103], v[50:51], v[96:97], v[114:115] op_sel_hi:[1,0,1]
	v_pk_fma_f32 v[112:113], v[48:49], v[96:97], v[118:119] op_sel_hi:[1,0,1]
	v_pk_fma_f32 v[96:97], v[50:51], v[60:61], v[104:105] op_sel_hi:[1,0,1]
	v_pk_fma_f32 v[104:105], v[48:49], v[60:61], v[120:121] op_sel_hi:[1,0,1]
	s_waitcnt lgkmcnt(2)
	v_mov_b32_e32 v60, v101
	v_pk_fma_f32 v[114:115], v[50:51], v[98:99], v[122:123] op_sel_hi:[1,0,1]
	v_pk_fma_f32 v[116:117], v[48:49], v[98:99], v[124:125] op_sel_hi:[1,0,1]
	v_pk_fma_f32 v[90:91], v[50:51], v[98:99], v[90:91] op_sel:[0,1,0]
	v_pk_fma_f32 v[98:99], v[48:49], v[98:99], v[106:107] op_sel:[0,1,0]
	v_pk_fma_f32 v[106:107], v[50:51], v[100:101], v[128:129] op_sel_hi:[1,0,1]
	v_pk_fma_f32 v[118:119], v[48:49], v[100:101], v[126:127] op_sel_hi:[1,0,1]
	v_pk_fma_f32 v[100:101], v[50:51], v[60:61], v[108:109] op_sel_hi:[1,0,1]
	v_pk_fma_f32 v[92:93], v[48:49], v[60:61], v[92:93] op_sel_hi:[1,0,1]
	s_waitcnt lgkmcnt(1)
	v_pk_mul_f32 v[60:61], v[46:47], v[52:53] op_sel_hi:[1,0]
	v_pk_mul_f32 v[62:63], v[44:45], v[52:53] op_sel_hi:[1,0]
	v_pk_fma_f32 v[50:51], v[50:51], v[76:77], v[60:61] op_sel_hi:[1,0,1]
	v_pk_fma_f32 v[48:49], v[48:49], v[76:77], v[62:63] op_sel_hi:[1,0,1]
	v_pk_fma_f32 v[50:51], v[42:43], v[52:53], v[50:51] op_sel:[0,1,0]
	v_pk_fma_f32 v[48:49], v[40:41], v[52:53], v[48:49] op_sel:[0,1,0]
	v_pk_fma_f32 v[50:51], v[38:39], v[54:55], v[50:51] op_sel_hi:[1,0,1]
	v_pk_fma_f32 v[48:49], v[36:37], v[54:55], v[48:49] op_sel_hi:[1,0,1]
	v_mov_b32_e32 v52, v55
	v_pk_fma_f32 v[50:51], v[34:35], v[52:53], v[50:51] op_sel_hi:[1,0,1]
	v_pk_fma_f32 v[48:49], v[32:33], v[52:53], v[48:49] op_sel_hi:[1,0,1]
	s_waitcnt lgkmcnt(0)
; #define LAS __attribute__((address_space(3)))
; template <bool STORE> __device__ __forceinline__ void ret_sample_item(LAS unsigned char* lds, int db, int h, bf16* Qb, const bf16* Kb, const bf16* Vb, const bf16* Gb, const f32x2* tab, const float* s_in, float* s_out) {
;     ...
;         for (int dl = 0; dl < 8; ++dl) {
;             const int d = dg * 8 + dl; const f32x4 s = st[dl];
;             const f32x4 qa = *(const LAS f32x4*)(qT + d * 8), qb = *(const LAS f32x4*)(qT + d * 8 + 4);
;             const f32x4 ka = *(const LAS f32x4*)(kT + d * 8), kb = *(const LAS f32x4*)(kT + d * 8 + 4);
;             cr[0] += s * qa.x; cr[1] += s * qa.y; cr[2] += s * qa.z; cr[3] += s * qa.w; cr[4] += s * qb.x; cr[5] += s * qb.y; cr[6] += s * qb.z; cr[7] += s * qb.w;
;             f32x4 sn = s * g8;
;             sn += vv[0] * ka.x; sn += vv[1] * ka.y; sn += vv[2] * ka.z; sn += vv[3] * ka.w; sn += vv[4] * kb.x; sn += vv[5] * kb.y; sn += vv[6] * kb.z; sn += vv[7] * kb.w;
;             if (STORE) *(f32x4*)(op + (size_t)dl * HD) = sn;
	v_pk_fma_f32 v[50:51], v[30:31], v[56:57], v[50:51] op_sel_hi:[1,0,1]
	v_pk_fma_f32 v[48:49], v[28:29], v[56:57], v[48:49] op_sel_hi:[1,0,1]
	v_pk_fma_f32 v[50:51], v[26:27], v[56:57], v[50:51] op_sel:[0,1,0]
	v_pk_fma_f32 v[48:49], v[24:25], v[56:57], v[48:49] op_sel:[0,1,0]
	v_pk_fma_f32 v[50:51], v[22:23], v[58:59], v[50:51] op_sel_hi:[1,0,1]
	v_pk_fma_f32 v[48:49], v[20:21], v[58:59], v[48:49] op_sel_hi:[1,0,1]
	v_mov_b32_e32 v52, v59
	v_pk_fma_f32 v[50:51], v[18:19], v[52:53], v[50:51] op_sel_hi:[1,0,1]
	v_pk_fma_f32 v[48:49], v[16:17], v[52:53], v[48:49] op_sel_hi:[1,0,1]
	ds_read_b128 v[52:55], v85 offset:128
	global_store_dwordx4 v[74:75], v[48:51], off offset:1536 sc1
	ds_read_b128 v[48:51], v85 offset:144
	ds_read_b128 v[56:59], v85 offset:4224
	ds_read_b128 v[60:63], v85 offset:4240
	v_readlane_b32 s8, v255, 17
	v_readlane_b32 s9, v255, 18
	s_waitcnt vmcnt(7) lgkmcnt(3)
	v_pk_fma_f32 v[108:109], v[14:15], v[52:53], v[110:111] op_sel:[0,1,0]
	v_pk_fma_f32 v[110:111], v[12:13], v[54:55], v[112:113] op_sel_hi:[1,0,1]
	s_waitcnt lgkmcnt(2)
	v_pk_fma_f32 v[112:113], v[12:13], v[48:49], v[116:117] op_sel_hi:[1,0,1]
	v_pk_fma_f32 v[114:115], v[14:15], v[48:49], v[114:115] op_sel_hi:[1,0,1]
	v_pk_fma_f32 v[98:99], v[12:13], v[48:49], v[98:99] op_sel:[0,1,0]
	v_pk_fma_f32 v[90:91], v[14:15], v[48:49], v[90:91] op_sel:[0,1,0]
	v_mov_b32_e32 v48, v51
	v_pk_fma_f32 v[88:89], v[12:13], v[52:53], v[88:89] op_sel_hi:[1,0,1]
	v_pk_fma_f32 v[86:87], v[14:15], v[52:53], v[86:87] op_sel_hi:[1,0,1]
	v_pk_fma_f32 v[94:95], v[12:13], v[52:53], v[94:95] op_sel:[0,1,0]
	v_mov_b32_e32 v52, v55
	v_pk_fma_f32 v[116:117], v[12:13], v[50:51], v[118:119] op_sel_hi:[1,0,1]
	v_pk_fma_f32 v[106:107], v[14:15], v[50:51], v[106:107] op_sel_hi:[1,0,1]
	v_pk_fma_f32 v[92:93], v[12:13], v[48:49], v[92:93] op_sel_hi:[1,0,1]
	v_pk_fma_f32 v[100:101], v[14:15], v[48:49], v[100:101] op_sel_hi:[1,0,1]
	s_waitcnt lgkmcnt(1)
	v_pk_mul_f32 v[48:49], v[46:47], v[56:57] op_sel_hi:[1,0]
	v_pk_mul_f32 v[50:51], v[44:45], v[56:57] op_sel_hi:[1,0]
	v_pk_fma_f32 v[102:103], v[14:15], v[54:55], v[102:103] op_sel_hi:[1,0,1]
	v_pk_fma_f32 v[104:105], v[12:13], v[52:53], v[104:105] op_sel_hi:[1,0,1]
	v_pk_fma_f32 v[96:97], v[14:15], v[52:53], v[96:97] op_sel_hi:[1,0,1]
	v_pk_fma_f32 v[14:15], v[76:77], v[14:15], v[48:49] op_sel_hi:[0,1,1]
	v_pk_fma_f32 v[12:13], v[76:77], v[12:13], v[50:51] op_sel_hi:[0,1,1]
	v_pk_fma_f32 v[14:15], v[42:43], v[56:57], v[14:15] op_sel:[0,1,0]
	v_pk_fma_f32 v[12:13], v[40:41], v[56:57], v[12:13] op_sel:[0,1,0]
	v_pk_fma_f32 v[14:15], v[38:39], v[58:59], v[14:15] op_sel_hi:[1,0,1]
	v_pk_fma_f32 v[12:13], v[36:37], v[58:59], v[12:13] op_sel_hi:[1,0,1]
	v_mov_b32_e32 v48, v59
	v_pk_fma_f32 v[14:15], v[34:35], v[48:49], v[14:15] op_sel_hi:[1,0,1]
	v_pk_fma_f32 v[12:13], v[32:33], v[48:49], v[12:13] op_sel_hi:[1,0,1]
	s_waitcnt lgkmcnt(0)
	v_pk_fma_f32 v[14:15], v[30:31], v[60:61], v[14:15] op_sel_hi:[1,0,1]
	v_pk_fma_f32 v[12:13], v[28:29], v[60:61], v[12:13] op_sel_hi:[1,0,1]
	v_pk_fma_f32 v[14:15], v[26:27], v[60:61], v[14:15] op_sel:[0,1,0]
	v_pk_fma_f32 v[12:13], v[24:25], v[60:61], v[12:13] op_sel:[0,1,0]
	v_pk_fma_f32 v[14:15], v[22:23], v[62:63], v[14:15] op_sel_hi:[1,0,1]
	v_pk_fma_f32 v[12:13], v[20:21], v[62:63], v[12:13] op_sel_hi:[1,0,1]
	v_mov_b32_e32 v48, v63
	v_pk_fma_f32 v[14:15], v[18:19], v[48:49], v[14:15] op_sel_hi:[1,0,1]
	v_pk_fma_f32 v[12:13], v[16:17], v[48:49], v[12:13] op_sel_hi:[1,0,1]
	ds_read_b128 v[48:51], v85 offset:160
	global_store_dwordx4 v[74:75], v[12:15], off offset:2048 sc1
	ds_read_b128 v[12:15], v85 offset:176
	ds_read_b128 v[52:55], v85 offset:4256
	ds_read_b128 v[56:59], v85 offset:4272
	s_waitcnt vmcnt(7) lgkmcnt(3)
	v_pk_fma_f32 v[60:61], v[10:11], v[48:49], v[86:87] op_sel_hi:[1,0,1]
	v_pk_fma_f32 v[62:63], v[8:9], v[48:49], v[88:89] op_sel_hi:[1,0,1]
	v_pk_fma_f32 v[86:87], v[10:11], v[48:49], v[108:109] op_sel:[0,1,0]
	v_pk_fma_f32 v[88:89], v[8:9], v[48:49], v[94:95] op_sel:[0,1,0]
	v_pk_fma_f32 v[94:95], v[10:11], v[50:51], v[102:103] op_sel_hi:[1,0,1]
	v_pk_fma_f32 v[102:103], v[8:9], v[50:51], v[110:111] op_sel_hi:[1,0,1]
	s_waitcnt lgkmcnt(2)
	v_pk_fma_f32 v[108:109], v[10:11], v[12:13], v[114:115] op_sel_hi:[1,0,1]
	v_pk_fma_f32 v[110:111], v[8:9], v[12:13], v[112:113] op_sel_hi:[1,0,1]
	v_pk_fma_f32 v[90:91], v[10:11], v[12:13], v[90:91] op_sel:[0,1,0]
	v_pk_fma_f32 v[98:99], v[8:9], v[12:13], v[98:99] op_sel:[0,1,0]
	v_mov_b32_e32 v12, v15
	v_mov_b32_e32 v48, v51
	v_pk_fma_f32 v[106:107], v[10:11], v[14:15], v[106:107] op_sel_hi:[1,0,1]
	v_pk_fma_f32 v[112:113], v[8:9], v[14:15], v[116:117] op_sel_hi:[1,0,1]
	v_pk_fma_f32 v[100:101], v[10:11], v[12:13], v[100:101] op_sel_hi:[1,0,1]
	v_pk_fma_f32 v[92:93], v[8:9], v[12:13], v[92:93] op_sel_hi:[1,0,1]
	s_waitcnt lgkmcnt(1)
	v_pk_mul_f32 v[12:13], v[46:47], v[52:53] op_sel_hi:[1,0]
	v_pk_mul_f32 v[14:15], v[44:45], v[52:53] op_sel_hi:[1,0]
	v_pk_fma_f32 v[96:97], v[10:11], v[48:49], v[96:97] op_sel_hi:[1,0,1]
	v_pk_fma_f32 v[104:105], v[8:9], v[48:49], v[104:105] op_sel_hi:[1,0,1]
	v_pk_fma_f32 v[10:11], v[76:77], v[10:11], v[12:13] op_sel_hi:[0,1,1]
	v_pk_fma_f32 v[8:9], v[76:77], v[8:9], v[14:15] op_sel_hi:[0,1,1]
	v_pk_fma_f32 v[10:11], v[42:43], v[52:53], v[10:11] op_sel:[0,1,0]
	v_pk_fma_f32 v[8:9], v[40:41], v[52:53], v[8:9] op_sel:[0,1,0]
	v_pk_fma_f32 v[10:11], v[38:39], v[54:55], v[10:11] op_sel_hi:[1,0,1]
	v_pk_fma_f32 v[8:9], v[36:37], v[54:55], v[8:9] op_sel_hi:[1,0,1]
	v_mov_b32_e32 v12, v55
	v_pk_fma_f32 v[10:11], v[34:35], v[12:13], v[10:11] op_sel_hi:[1,0,1]
	v_pk_fma_f32 v[8:9], v[32:33], v[12:13], v[8:9] op_sel_hi:[1,0,1]
	s_waitcnt lgkmcnt(0)
; #define LAS __attribute__((address_space(3)))
; template <bool STORE> __device__ __forceinline__ void ret_sample_item(LAS unsigned char* lds, int db, int h, bf16* Qb, const bf16* Kb, const bf16* Vb, const bf16* Gb, const f32x2* tab, const float* s_in, float* s_out) {
;     ...
;         for (int dl = 0; dl < 8; ++dl) {
;             const int d = dg * 8 + dl; const f32x4 s = st[dl];
;             const f32x4 qa = *(const LAS f32x4*)(qT + d * 8), qb = *(const LAS f32x4*)(qT + d * 8 + 4);
;             const f32x4 ka = *(const LAS f32x4*)(kT + d * 8), kb = *(const LAS f32x4*)(kT + d * 8 + 4);
;             cr[0] += s * qa.x; cr[1] += s * qa.y; cr[2] += s * qa.z; cr[3] += s * qa.w; cr[4] += s * qb.x; cr[5] += s * qb.y; cr[6] += s * qb.z; cr[7] += s * qb.w;
;             f32x4 sn = s * g8;
;             sn += vv[0] * ka.x; sn += vv[1] * ka.y; sn += vv[2] * ka.z; sn += vv[3] * ka.w; sn += vv[4] * kb.x; sn += vv[5] * kb.y; sn += vv[6] * kb.z; sn += vv[7] * kb.w;
;             if (STORE) *(f32x4*)(op + (size_t)dl * HD) = sn;
;         }
; #pragma unroll
;         for (int i = 0; i < 8; ++i) *(LAS f32x4*)(red + (dg * 8 + i) * 128 + e4) = cr[i];
;     }
;     __syncthreads();
	v_pk_fma_f32 v[10:11], v[30:31], v[56:57], v[10:11] op_sel_hi:[1,0,1]
	v_pk_fma_f32 v[8:9], v[28:29], v[56:57], v[8:9] op_sel_hi:[1,0,1]
	v_pk_fma_f32 v[10:11], v[26:27], v[56:57], v[10:11] op_sel:[0,1,0]
	v_pk_fma_f32 v[8:9], v[24:25], v[56:57], v[8:9] op_sel:[0,1,0]
	v_pk_fma_f32 v[10:11], v[22:23], v[58:59], v[10:11] op_sel_hi:[1,0,1]
	v_pk_fma_f32 v[8:9], v[20:21], v[58:59], v[8:9] op_sel_hi:[1,0,1]
	v_mov_b32_e32 v12, v59
	v_pk_fma_f32 v[10:11], v[18:19], v[12:13], v[10:11] op_sel_hi:[1,0,1]
	v_pk_fma_f32 v[8:9], v[16:17], v[12:13], v[8:9] op_sel_hi:[1,0,1]
	ds_read_b128 v[12:15], v85 offset:192
	global_store_dwordx4 v[74:75], v[8:11], off offset:2560 sc1
	ds_read_b128 v[8:11], v85 offset:208
	ds_read_b128 v[48:51], v85 offset:4288
	ds_read_b128 v[52:55], v85 offset:4304
	s_waitcnt vmcnt(7) lgkmcnt(3)
	v_pk_fma_f32 v[56:57], v[4:5], v[12:13], v[62:63] op_sel_hi:[1,0,1]
	v_pk_fma_f32 v[58:59], v[6:7], v[12:13], v[60:61] op_sel_hi:[1,0,1]
	v_pk_fma_f32 v[60:61], v[4:5], v[12:13], v[88:89] op_sel:[0,1,0]
	v_pk_fma_f32 v[62:63], v[6:7], v[12:13], v[86:87] op_sel:[0,1,0]
	v_mov_b32_e32 v12, v15
	v_pk_fma_f32 v[86:87], v[4:5], v[14:15], v[102:103] op_sel_hi:[1,0,1]
	v_pk_fma_f32 v[88:89], v[6:7], v[14:15], v[94:95] op_sel_hi:[1,0,1]
	v_pk_fma_f32 v[94:95], v[4:5], v[12:13], v[104:105] op_sel_hi:[1,0,1]
	s_waitcnt lgkmcnt(2)
	v_pk_fma_f32 v[102:103], v[4:5], v[8:9], v[110:111] op_sel_hi:[1,0,1]
	v_pk_fma_f32 v[104:105], v[6:7], v[8:9], v[108:109] op_sel_hi:[1,0,1]
	v_pk_fma_f32 v[98:99], v[4:5], v[8:9], v[98:99] op_sel:[0,1,0]
	v_pk_fma_f32 v[90:91], v[6:7], v[8:9], v[90:91] op_sel:[0,1,0]
	v_mov_b32_e32 v8, v11
	v_pk_fma_f32 v[108:109], v[4:5], v[10:11], v[112:113] op_sel_hi:[1,0,1]
	v_pk_fma_f32 v[106:107], v[6:7], v[10:11], v[106:107] op_sel_hi:[1,0,1]
	v_pk_fma_f32 v[110:111], v[4:5], v[8:9], v[92:93] op_sel_hi:[1,0,1]
	v_pk_fma_f32 v[100:101], v[6:7], v[8:9], v[100:101] op_sel_hi:[1,0,1]
	s_waitcnt lgkmcnt(1)
	v_pk_mul_f32 v[8:9], v[46:47], v[48:49] op_sel_hi:[1,0]
	v_pk_mul_f32 v[10:11], v[44:45], v[48:49] op_sel_hi:[1,0]
	v_pk_fma_f32 v[96:97], v[6:7], v[12:13], v[96:97] op_sel_hi:[1,0,1]
	v_pk_fma_f32 v[6:7], v[76:77], v[6:7], v[8:9] op_sel_hi:[0,1,1]
	v_pk_fma_f32 v[4:5], v[76:77], v[4:5], v[10:11] op_sel_hi:[0,1,1]
	v_pk_fma_f32 v[6:7], v[42:43], v[48:49], v[6:7] op_sel:[0,1,0]
	v_pk_fma_f32 v[4:5], v[40:41], v[48:49], v[4:5] op_sel:[0,1,0]
	v_pk_fma_f32 v[6:7], v[38:39], v[50:51], v[6:7] op_sel_hi:[1,0,1]
	v_pk_fma_f32 v[4:5], v[36:37], v[50:51], v[4:5] op_sel_hi:[1,0,1]
	v_mov_b32_e32 v8, v51
	v_pk_fma_f32 v[6:7], v[34:35], v[8:9], v[6:7] op_sel_hi:[1,0,1]
	v_pk_fma_f32 v[4:5], v[32:33], v[8:9], v[4:5] op_sel_hi:[1,0,1]
	s_waitcnt lgkmcnt(0)
	v_pk_fma_f32 v[6:7], v[30:31], v[52:53], v[6:7] op_sel_hi:[1,0,1]
	v_pk_fma_f32 v[4:5], v[28:29], v[52:53], v[4:5] op_sel_hi:[1,0,1]
	v_pk_fma_f32 v[6:7], v[26:27], v[52:53], v[6:7] op_sel:[0,1,0]
	v_pk_fma_f32 v[4:5], v[24:25], v[52:53], v[4:5] op_sel:[0,1,0]
	v_pk_fma_f32 v[6:7], v[22:23], v[54:55], v[6:7] op_sel_hi:[1,0,1]
	v_pk_fma_f32 v[4:5], v[20:21], v[54:55], v[4:5] op_sel_hi:[1,0,1]
	v_mov_b32_e32 v8, v55
	v_pk_fma_f32 v[6:7], v[18:19], v[8:9], v[6:7] op_sel_hi:[1,0,1]
	v_pk_fma_f32 v[4:5], v[16:17], v[8:9], v[4:5] op_sel_hi:[1,0,1]
	v_mov_b32_e32 v8, 0xe0
	v_lshl_or_b32 v8, v83, 5, v8
	v_add_u32_e32 v48, 0, v8
	ds_read_b128 v[8:11], v48
	global_store_dwordx4 v[74:75], v[4:7], off offset:3072 sc1
	ds_read_b128 v[4:7], v48 offset:16
	ds_read_b128 v[12:15], v48 offset:4096
	ds_read_b128 v[48:51], v48 offset:4112
	s_waitcnt vmcnt(7) lgkmcnt(3)
	v_pk_fma_f32 v[54:55], v[2:3], v[8:9], v[58:59] op_sel_hi:[1,0,1]
	v_pk_fma_f32 v[52:53], v[0:1], v[8:9], v[56:57] op_sel_hi:[1,0,1]
	v_pk_fma_f32 v[58:59], v[2:3], v[8:9], v[62:63] op_sel:[0,1,0]
	v_pk_fma_f32 v[56:57], v[0:1], v[8:9], v[60:61] op_sel:[0,1,0]
	v_pk_fma_f32 v[62:63], v[2:3], v[10:11], v[88:89] op_sel_hi:[1,0,1]
	v_pk_fma_f32 v[60:61], v[0:1], v[10:11], v[86:87] op_sel_hi:[1,0,1]
	v_mov_b32_e32 v8, v11
	s_waitcnt lgkmcnt(2)
	v_pk_fma_f32 v[88:89], v[2:3], v[4:5], v[104:105] op_sel_hi:[1,0,1]
	v_pk_fma_f32 v[86:87], v[0:1], v[4:5], v[102:103] op_sel_hi:[1,0,1]
	v_pk_fma_f32 v[92:93], v[2:3], v[4:5], v[90:91] op_sel:[0,1,0]
	v_pk_fma_f32 v[90:91], v[0:1], v[4:5], v[98:99] op_sel:[0,1,0]
	v_mov_b32_e32 v4, v7
	s_waitcnt lgkmcnt(1)
	v_pk_mul_f32 v[46:47], v[46:47], v[12:13] op_sel_hi:[1,0]
	v_pk_mul_f32 v[44:45], v[44:45], v[12:13] op_sel_hi:[1,0]
	v_pk_fma_f32 v[10:11], v[2:3], v[8:9], v[96:97] op_sel_hi:[1,0,1]
	v_pk_fma_f32 v[8:9], v[0:1], v[8:9], v[94:95] op_sel_hi:[1,0,1]
	v_pk_fma_f32 v[96:97], v[2:3], v[6:7], v[106:107] op_sel_hi:[1,0,1]
	v_pk_fma_f32 v[94:95], v[0:1], v[6:7], v[108:109] op_sel_hi:[1,0,1]
	v_pk_fma_f32 v[6:7], v[2:3], v[4:5], v[100:101] op_sel_hi:[1,0,1]
	v_pk_fma_f32 v[4:5], v[0:1], v[4:5], v[110:111] op_sel_hi:[1,0,1]
	v_pk_fma_f32 v[2:3], v[76:77], v[2:3], v[46:47] op_sel_hi:[0,1,1]
	v_pk_fma_f32 v[0:1], v[76:77], v[0:1], v[44:45] op_sel_hi:[0,1,1]
	v_pk_fma_f32 v[2:3], v[42:43], v[12:13], v[2:3] op_sel:[0,1,0]
	v_pk_fma_f32 v[0:1], v[40:41], v[12:13], v[0:1] op_sel:[0,1,0]
	v_pk_fma_f32 v[2:3], v[38:39], v[14:15], v[2:3] op_sel_hi:[1,0,1]
	v_pk_fma_f32 v[0:1], v[36:37], v[14:15], v[0:1] op_sel_hi:[1,0,1]
	v_mov_b32_e32 v12, v15
	v_pk_fma_f32 v[2:3], v[34:35], v[12:13], v[2:3] op_sel_hi:[1,0,1]
	v_pk_fma_f32 v[0:1], v[32:33], v[12:13], v[0:1] op_sel_hi:[1,0,1]
	s_waitcnt lgkmcnt(0)
	v_pk_fma_f32 v[2:3], v[30:31], v[48:49], v[2:3] op_sel_hi:[1,0,1]
	v_pk_fma_f32 v[0:1], v[28:29], v[48:49], v[0:1] op_sel_hi:[1,0,1]
	v_pk_fma_f32 v[2:3], v[26:27], v[48:49], v[2:3] op_sel:[0,1,0]
	v_pk_fma_f32 v[0:1], v[24:25], v[48:49], v[0:1] op_sel:[0,1,0]
	v_pk_fma_f32 v[2:3], v[22:23], v[50:51], v[2:3] op_sel_hi:[1,0,1]
	v_pk_fma_f32 v[0:1], v[20:21], v[50:51], v[0:1] op_sel_hi:[1,0,1]
	v_mov_b32_e32 v12, v51
	v_pk_fma_f32 v[2:3], v[18:19], v[12:13], v[2:3] op_sel_hi:[1,0,1]
	v_pk_fma_f32 v[0:1], v[16:17], v[12:13], v[0:1] op_sel_hi:[1,0,1]
	global_store_dwordx4 v[74:75], v[0:3], off offset:3584 sc1
	v_lshl_add_u32 v48, v77, 2, 0
	s_nop 0
	v_lshl_add_u32 v0, v72, 9, v73
	ds_write_b128 v0, v[52:55] offset:12544
	ds_write_b128 v0, v[56:59] offset:13056
	ds_write_b128 v0, v[60:63] offset:13568
	ds_write_b128 v0, v[8:11] offset:14080
	ds_write_b128 v0, v[86:89] offset:14592
	ds_write_b128 v0, v[90:93] offset:15104
	ds_write_b128 v0, v[94:97] offset:15616
	v_mov_b32_e32 v0, 0xe00
	v_lshl_or_b32 v0, v83, 9, v0
	v_add_u32_e32 v0, v73, v0
	ds_write_b128 v0, v[4:7] offset:12544
	v_add_u32_e32 v0, 1, v79
	v_cvt_f32_i32_e32 v0, v0
	v_lshl_add_u32 v2, v79, 9, v48
	s_waitcnt lgkmcnt(0)
	s_barrier
; __device__ __forceinline__ unsigned cvt_pk_bf16(float lo, float hi) { unsigned r; asm volatile("v_cvt_pk_bf16_f32 %0, %1, %2" : "=v"(r) : "v"(lo), "v"(hi)); return r; }
; template <bool STORE> __device__ __forceinline__ void ret_sample_item(LAS unsigned char* lds, int db, int h, bf16* Qb, const bf16* Kb, const bf16* Vb, const bf16* Gb, const f32x2* tab, const float* s_in, float* s_out) {
;     ...
;     {
;         const int i = w; float o[2];
; #pragma unroll
;         for (int t = 0; t < 2; ++t) {
;             const int e = lane + 64 * t;
;             float cr = 0.f;
; #pragma unroll
;             for (int g = 0; g < 16; ++g) cr += red[(g * 8 + i) * 128 + e];
;             float x = cr * __expf(lg * (float)(i + 1));
; #pragma unroll
;             for (int j = 0; j < 8; ++j) x += sc[i * 8 + j] * vS[j * 128 + e];
;             o[t] = x;
;         }
;         const float mean = wave_sum(o[0] + o[1]) * (1.f / HD);
;         const float d0 = o[0] - mean, d1 = o[1] - mean;
;         const float var = wave_sum(d0 * d0 + d1 * d1) * (1.f / HD);
;         const float rstd = __builtin_amdgcn_rsqf(var + EPS);
;         const size_t roff = (size_t)(row0 + i) * DM + h * HD;
;         const float g0 = __builtin_bit_cast(float, (unsigned)Gb[roff + lane] << 16), g1 = __builtin_bit_cast(float, (unsigned)Gb[roff + lane + 64] << 16);
;         if (STORE) { Qb[roff + lane] = (bf16)(cvt_pk_bf16(g0 * d0 * rstd, 0.f) & 0xffffu);
;         Qb[roff + lane + 64] = (bf16)(cvt_pk_bf16(g1 * d1 * rstd, 0.f) & 0xffffu); }
;         else if (g0 * d0 * rstd + g1 * d1 * rstd == 12345.678f) Qb[roff + lane] = 0;
;     }
;     __syncthreads();
	ds_read2st64_b32 v[8:9], v2 offset0:49 offset1:50
	ds_read2st64_b32 v[10:11], v2 offset0:65 offset1:66
	ds_read2st64_b32 v[12:13], v2 offset0:81 offset1:82
	v_mul_f32_e32 v0, s20, v0
	ds_read2st64_b32 v[14:15], v2 offset0:97 offset1:98
	v_mul_f32_e32 v0, 0x3fb8aa3b, v0
	v_exp_f32_e32 v50, v0
	s_waitcnt lgkmcnt(3)
	v_add_f32_e32 v0, 0, v8
	s_waitcnt lgkmcnt(2)
	v_add_f32_e32 v0, v0, v10
	ds_read2st64_b32 v[16:17], v2 offset0:113 offset1:114
	ds_read2st64_b32 v[18:19], v2 offset0:129 offset1:130
	ds_read2st64_b32 v[20:21], v2 offset0:145 offset1:146
	s_waitcnt lgkmcnt(4)
	v_add_f32_e32 v0, v0, v12
	ds_read2st64_b32 v[22:23], v2 offset0:161 offset1:162
	ds_read2st64_b32 v[24:25], v2 offset0:177 offset1:178
	s_waitcnt lgkmcnt(5)
	v_add_f32_e32 v0, v0, v14
	s_waitcnt lgkmcnt(4)
	v_add_f32_e32 v0, v0, v16
	s_waitcnt lgkmcnt(3)
	v_add_f32_e32 v0, v0, v18
	s_waitcnt lgkmcnt(2)
	v_add_f32_e32 v0, v0, v20
	ds_read2st64_b32 v[26:27], v2 offset0:193 offset1:194
	ds_read2st64_b32 v[28:29], v2 offset0:209 offset1:210
	ds_read2st64_b32 v[30:31], v2 offset0:225 offset1:226
	s_waitcnt lgkmcnt(4)
	v_add_f32_e32 v0, v0, v22
	v_add_u32_e32 v3, 0x3100, v2
	s_waitcnt lgkmcnt(3)
	v_add_f32_e32 v0, v0, v24
	ds_read2st64_b32 v[32:33], v2 offset0:241 offset1:242
	v_add_f32_e32 v9, 0, v9
	s_waitcnt lgkmcnt(3)
	v_add_f32_e32 v5, v0, v26
	ds_read2st64_b32 v[0:1], v3 offset0:208 offset1:224
	v_add_f32_e32 v9, v9, v11
	v_add_f32_e32 v9, v9, v13
	s_waitcnt lgkmcnt(3)
	v_add_f32_e32 v5, v5, v28
	ds_read_b32 v3, v3 offset:61440
	v_add_f32_e32 v9, v9, v15
	s_waitcnt lgkmcnt(3)
	v_add_f32_e32 v5, v5, v30
	v_add_f32_e32 v9, v9, v17
	s_waitcnt lgkmcnt(2)
	v_add_f32_e32 v5, v5, v32
	v_add_f32_e32 v9, v9, v19
	s_waitcnt lgkmcnt(1)
	v_add_f32_e32 v0, v5, v0
	v_add_f32_e32 v9, v9, v21
	v_add_u32_e32 v4, 0, v84
	v_add_f32_e32 v0, v0, v1
	v_add_u32_e32 v8, 0x3200, v2
	v_add_f32_e32 v9, v9, v23
	ds_read_b32 v10, v8 offset:61440
	s_waitcnt lgkmcnt(1)
	v_add_f32_e32 v12, v0, v3
	ds_read2st64_b32 v[34:35], v48 offset0:32 offset1:33
	ds_read_b128 v[0:3], v4 offset:12288
	ds_read_b128 v[4:7], v4 offset:12304
	ds_read2st64_b32 v[36:37], v48 offset0:34 offset1:35
	ds_read2st64_b32 v[38:39], v48 offset0:36 offset1:37
	ds_read2st64_b32 v[40:41], v48 offset0:38 offset1:39
	ds_read2st64_b32 v[42:43], v48 offset0:40 offset1:41
	ds_read2st64_b32 v[44:45], v48 offset0:42 offset1:43
	ds_read2st64_b32 v[46:47], v48 offset0:44 offset1:45
	ds_read2st64_b32 v[48:49], v48 offset0:46 offset1:47
	v_add_f32_e32 v11, v9, v25
	ds_read2st64_b32 v[8:9], v8 offset0:208 offset1:224
	v_add_f32_e32 v11, v11, v27
	v_add_f32_e32 v11, v11, v29
	v_add_f32_e32 v11, v11, v31
	v_add_f32_e32 v11, v11, v33
	s_waitcnt lgkmcnt(0)
	v_add_f32_e32 v8, v11, v8
	v_add_f32_e32 v8, v8, v9
	v_mul_f32_e32 v14, v0, v34
	v_add_f32_e32 v8, v8, v10
	v_mul_f32_e32 v9, v0, v35
	v_fmac_f32_e32 v14, v50, v12
	v_fmac_f32_e32 v9, v50, v8
	v_fmac_f32_e32 v14, v1, v36
	v_fmac_f32_e32 v9, v1, v37
	v_fmac_f32_e32 v14, v2, v38
	v_fmac_f32_e32 v9, v2, v39
	v_fmac_f32_e32 v14, v3, v40
	v_fmac_f32_e32 v9, v3, v41
	v_fmac_f32_e32 v14, v4, v42
	v_fmac_f32_e32 v9, v4, v43
	v_fmac_f32_e32 v14, v5, v44
	v_fmac_f32_e32 v9, v5, v45
	v_xor_b32_e32 v1, 1, v208
	v_fmac_f32_e32 v14, v6, v46
	v_fmac_f32_e32 v9, v6, v47
	v_cmp_lt_i32_e32 vcc, v1, v82
	v_fmac_f32_e32 v14, v7, v48
	v_fmac_f32_e32 v9, v7, v49
	v_cndmask_b32_e32 v1, v208, v1, vcc
	v_add_f32_e32 v0, v14, v9
	v_lshlrev_b32_e32 v4, 2, v1
	ds_bpermute_b32 v1, v4, v0
	v_xor_b32_e32 v6, 2, v208
	v_lshl_add_u64 v[2:3], v[70:71], 1, s[8:9]
	v_cmp_lt_i32_e32 vcc, v6, v82
	s_waitcnt lgkmcnt(0)
	v_add_f32_e32 v5, v0, v1
	v_lshl_add_u64 v[0:1], v[68:69], 1, s[8:9]
	global_load_ushort v0, v[0:1], off
	s_nop 0
	global_load_ushort v1, v[2:3], off
	v_cndmask_b32_e32 v2, v208, v6, vcc
	v_lshlrev_b32_e32 v2, 2, v2
	ds_bpermute_b32 v3, v2, v5
	v_readlane_b32 s8, v254, 33
	s_add_i32 s19, s19, s8
	s_cmpk_gt_i32 s19, 0x3ff
	s_waitcnt lgkmcnt(0)
	v_add_f32_e32 v3, v5, v3
	v_xor_b32_e32 v5, 4, v208
	v_cmp_lt_i32_e32 vcc, v5, v82
	s_waitcnt vmcnt(1)
	v_lshlrev_b32_e32 v0, 16, v0
	v_cndmask_b32_e32 v5, v208, v5, vcc
	v_lshlrev_b32_e32 v5, 2, v5
	ds_bpermute_b32 v6, v5, v3
	s_waitcnt vmcnt(0)
	v_lshlrev_b32_e32 v1, 16, v1
	s_waitcnt lgkmcnt(0)
	v_add_f32_e32 v3, v3, v6
	ds_bpermute_b32 v6, v78, v3
	s_waitcnt lgkmcnt(0)
	v_add_f32_e32 v3, v3, v6
	ds_bpermute_b32 v6, v80, v3
	s_waitcnt lgkmcnt(0)
	v_add_f32_e32 v3, v3, v6
	ds_bpermute_b32 v6, v81, v3
	s_waitcnt lgkmcnt(0)
	v_add_f32_e32 v3, v3, v6
	v_fmac_f32_e32 v9, 0xbc000000, v3
	v_fmac_f32_e32 v14, 0xbc000000, v3
	v_mul_f32_e32 v3, v9, v9
	v_fmac_f32_e32 v3, v14, v14
	ds_bpermute_b32 v4, v4, v3
	v_mul_f32_e32 v0, v14, v0
	s_waitcnt lgkmcnt(0)
	v_add_f32_e32 v3, v3, v4
	ds_bpermute_b32 v2, v2, v3
	s_waitcnt lgkmcnt(0)
	v_add_f32_e32 v2, v3, v2
	ds_bpermute_b32 v3, v5, v2
	s_waitcnt lgkmcnt(0)
	v_add_f32_e32 v2, v2, v3
	ds_bpermute_b32 v3, v78, v2
	s_waitcnt lgkmcnt(0)
	v_add_f32_e32 v2, v2, v3
	ds_bpermute_b32 v3, v80, v2
	s_waitcnt lgkmcnt(0)
	v_add_f32_e32 v2, v2, v3
	ds_bpermute_b32 v3, v81, v2
	s_waitcnt lgkmcnt(0)
	v_add_f32_e32 v2, v2, v3
	v_fmamk_f32 v2, v2, 0x3c000000, v207
	v_rsq_f32_e32 v2, v2
	s_nop 0
	v_mul_f32_e32 v0, v0, v2
	v_cvt_pk_bf16_f32 v0, v0, v189
	global_store_short v[64:65], v0, off
	v_mul_f32_e32 v0, v9, v1
	v_mul_f32_e32 v0, v0, v2
	v_cvt_pk_bf16_f32 v0, v0, v189
	global_store_short v[66:67], v0, off
	s_barrier
	s_cbranch_scc1 .LBB0_515
